# band attention loop rotated: next tile's LDS write and the following prefetch issued at the end of the iteration into the other LDS buffer; loop top is just the barrier
# baseline (speedup 1.0000x reference)
.LBB0_450:
	s_or_b64 exec, exec, s[26:27]
	s_ashr_i32 s23, s23, 8
	s_lshl_b32 s62, s23, 2
	s_add_i32 s23, s62, -8
	s_cmpk_gt_i32 s92, 0x2ff
	s_cselect_b32 s23, s23, 0
	s_or_b32 s24, s62, 3
	s_cmp_le_i32 s23, s24
	s_cbranch_scc0 .LBB0_465
	s_lshl_b32 s60, s23, 6
	s_add_i32 s60, s60, s93
	v_add_u32_e32 v4, s60, v150
	v_ashrrev_i32_e32 v5, 31, v4
	v_lshlrev_b64 v[4:5], 11, v[4:5]
	s_lshl_b64 s[26:27], s[16:17], 1
	v_lshl_add_u64 v[6:7], s[50:51], 0, v[4:5]
	v_lshl_add_u64 v[4:5], s[48:49], 0, v[4:5]
	v_lshl_add_u64 v[6:7], v[6:7], 0, s[26:27]
	v_lshl_add_u64 v[4:5], v[4:5], 0, s[26:27]
	v_lshl_add_u64 v[6:7], v[6:7], 0, v[108:109]
	v_lshl_add_u64 v[4:5], v[4:5], 0, v[108:109]
	s_add_i32 s62, s62, s29
	v_mov_b32_e32 v16, v3
	v_mov_b32_e32 v17, v3
	s_sub_i32 s64, s62, s23
	v_mov_b32_e32 v2, v3
	v_mov_b32_e32 v4, v3
	v_mov_b32_e32 v5, v3
	v_mov_b32_e32 v6, v3
	v_mov_b32_e32 v7, v3
	v_mov_b32_e32 v8, v3
	v_mov_b32_e32 v9, v3
	v_mov_b32_e32 v10, v3
	v_mov_b32_e32 v11, v3
	v_mov_b32_e32 v12, v3
	v_mov_b32_e32 v13, v3
	v_mov_b32_e32 v14, v3
	v_mov_b32_e32 v15, v3
	v_mov_b64_e32 v[48:49], v[16:17]
	v_mov_b64_e32 v[32:33], v[16:17]
	v_lshl_add_u64 v[124:125], v[110:111], 0, s[26:27]
	v_lshl_add_u64 v[126:127], v[112:113], 0, s[26:27]
	s_add_i32 s63, s62, -8
	v_lshl_add_u32 v119, s64, 6, v162
	v_add_u32_e32 v128, s60, v163
	v_mov_b32_e32 v173, 0xf149f2ca
	v_mov_b32_e32 v172, 0
	v_mov_b64_e32 v[46:47], v[14:15]
	v_mov_b64_e32 v[44:45], v[12:13]
	v_mov_b64_e32 v[42:43], v[10:11]
	v_mov_b64_e32 v[40:41], v[8:9]
	v_mov_b64_e32 v[38:39], v[6:7]
	v_mov_b64_e32 v[36:37], v[4:5]
	v_mov_b64_e32 v[34:35], v[2:3]
	v_mov_b64_e32 v[30:31], v[14:15]
	v_mov_b64_e32 v[28:29], v[12:13]
	v_mov_b64_e32 v[26:27], v[10:11]
	v_mov_b64_e32 v[24:25], v[8:9]
	v_mov_b64_e32 v[22:23], v[6:7]
	v_mov_b64_e32 v[20:21], v[4:5]
	v_mov_b64_e32 v[18:19], v[2:3]
	s_waitcnt vmcnt(0)
	v_add_u32_e32 v2, v114, v151
	ds_write_b128 v2, v[102:105]
	ds_write_b128 v164, v[98:101] offset:9216
	s_nop 1
	v_ashrrev_i32_e32 v129, 31, v128
	v_lshlrev_b64 v[4:5], 11, v[128:129]
	v_lshl_add_u64 v[6:7], v[126:127], 0, v[4:5]
	v_lshl_add_u64 v[4:5], v[124:125], 0, v[4:5]
	global_load_dwordx4 v[102:105], v[4:5], off
	global_load_dwordx4 v[98:101], v[6:7], off
	v_add_u32_e32 v128, 64, v128
.LBB0_452:
	s_cmp_ge_i32 s23, s24
	s_cselect_b64 s[26:27], -1, 0
	s_waitcnt lgkmcnt(0)
	s_barrier

.LBB0_463:
	s_add_i32 s23, s23, 1
	v_subrev_u32_e32 v119, 64, v119
	s_add_i32 s64, s64, -1
	s_and_b64 vcc, exec, s[26:27]
	s_cbranch_vccnz .LBB0_466
	v_xor_b32_e32 v114, 0x8000, v114
	v_xor_b32_e32 v164, 0x8000, v164
	v_xor_b32_e32 v165, 0x8000, v165
	v_xor_b32_e32 v153, 0x8000, v153
	v_mov_b32_e32 v173, v50
	s_waitcnt vmcnt(0)
	v_add_u32_e32 v2, v114, v151
	ds_write_b128 v2, v[102:105]
	ds_write_b128 v164, v[98:101] offset:9216
	s_nop 1
	s_cmp_ge_i32 s23, s24
	s_cbranch_scc1 .LBB0_452
	v_ashrrev_i32_e32 v129, 31, v128
	v_lshlrev_b64 v[4:5], 11, v[128:129]
	v_lshl_add_u64 v[6:7], v[126:127], 0, v[4:5]
	v_lshl_add_u64 v[4:5], v[124:125], 0, v[4:5]
	global_load_dwordx4 v[102:105], v[4:5], off
	global_load_dwordx4 v[98:101], v[6:7], off
	v_add_u32_e32 v128, 64, v128
	s_branch .LBB0_452
